# hand-written GDN chunk scan: 64 workgroups, state wave keeps -S in registers, operands straight from global one chunk ahead, one barrier per chunk
# speedup vs baseline: 1.0560x; 1.0321x over previous
; #define GLOBAL_AS __attribute__((address_space(1)))
; #define BIDX opaque_bid()
; #define EN(bit) if constexpr ((ENABLE >> (bit)) & 1)
; __global__ void __launch_bounds__(256, 2) mk(Params p_in, int ph_lo, int ph_hi) {
;     ...
;     long zoff = 0;
;     asm volatile("" : "+s"(zoff));
;     Params p;
; #pragma unroll
;     for (int i = 0; i < 21; ++i) p.in[i] = (const float*)((GLOBAL_AS const float*)(p_in.in[i]));
;     p.ws = (char*)((GLOBAL_AS char*)(p_in.ws + zoff));
;     p.out = (float*)((GLOBAL_AS float*)(p_in.out + zoff));
;     bf16_t* hb = (bf16_t*)(p.ws + OFF_HB);
;     bf16_t* wb = (bf16_t*)(p.ws + OFF_WB);
;     bf16_t* r0 = (bf16_t*)(p.ws + OFF_R0);
;     bf16_t* r1 = (bf16_t*)(p.ws + OFF_R1);
;     ...
;           const int nitems = 8 * (8 / NW);
;           if ((int)BIDX < nitems) {
;             EN(7) { scan_item(p, BIDX & 7, BIDX >> 3, smem); }
;           } else {
;             EN(2) { gemm_phase(hb, 1024, wb + WB_Z, 1024, 8, smem, EpiZ{r0 + R0_Z}, nitems); }
.LBB0_16:
	s_and_b32 s6, s48, 63
	s_cmp_eq_u32 s6, 0
	s_cselect_b64 s[12:13], -1, 0
	s_cmp_lg_u32 s6, 0
	s_cselect_b64 s[90:91], -1, 0
	s_ashr_i32 s92, s48, 3
	s_lshl_b32 s94, s48, 2
	s_sub_i32 s93, s48, 64
	s_lshl_b32 s8, s48, 4
	s_lshl_b32 s96, s48, 8
	s_cmp_gt_i32 s87, 1
	s_cselect_b64 s[30:31], -1, 0
	s_add_u32 s10, s84, 0xfd13200
	s_addc_u32 s11, s85, 0
	s_add_u32 s28, s84, 0xfd13400
	v_writelane_b32 v249, s10, 0
	s_addc_u32 s29, s85, 0
	s_load_dword s6, s[0:1], 0xc8
	v_writelane_b32 v249, s11, 1
	s_add_u32 s10, s84, 0xfd13500
	s_addc_u32 s11, s85, 0
	v_writelane_b32 v249, s10, 2
	s_mul_i32 s3, s49, s48
	s_waitcnt lgkmcnt(0)
	s_mul_i32 s6, s3, s6
	v_writelane_b32 v249, s11, 3
	s_add_u32 s10, s84, 0xfd13600
	s_addc_u32 s11, s85, 0
	v_writelane_b32 v249, s10, 4
	s_load_dwordx8 s[36:43], s[0:1], 0x80
	s_load_dwordx16 s[68:83], s[0:1], 0x0
	v_writelane_b32 v249, s11, 5
	s_add_u32 s10, s84, 0xfd13700
	s_addc_u32 s11, s85, 0
	v_writelane_b32 v249, s10, 6
	v_mov_b32_e32 v1, 0
	v_mbcnt_lo_u32_b32 v0, -1, 0
	v_writelane_b32 v249, s11, 7
	s_add_u32 s10, s84, 0xfd13800
	s_addc_u32 s11, s85, 0
	v_writelane_b32 v249, s10, 8
	v_mov_b32_e32 v186, 0x3f4ccccd
	v_mov_b32_e32 v208, 0x358637bd
	v_writelane_b32 v249, s11, 9
	s_add_u32 s10, s84, 0xfd13900
	s_addc_u32 s11, s85, 0
	v_writelane_b32 v249, s10, 10
	v_mov_b32_e32 v209, 0x3ecc95a3
	v_mov_b32_e32 v210, 0x3727c5ac
	v_writelane_b32 v249, s11, 11
	s_add_u32 s10, s84, 0xfd13a00
	s_addc_u32 s11, s85, 0
	v_writelane_b32 v249, s10, 12
	v_mov_b32_e32 v211, 1
	v_mov_b32_e32 v212, 0x3ff0000
	v_writelane_b32 v249, s11, 13
	s_add_u32 s10, s84, 0xfd13b00
	s_addc_u32 s11, s85, 0
	v_writelane_b32 v249, s10, 14
	v_mov_b32_e32 v213, 0x7f800000
	v_mov_b32_e32 v214, 0x41b17218
	v_writelane_b32 v249, s11, 15
	s_add_u32 s10, s84, 0xfd13c00
	s_addc_u32 s11, s85, 0
	v_writelane_b32 v249, s10, 16
	v_mbcnt_hi_u32_b32 v215, -1, v0
	v_mov_b32_e32 v216, 0x3e38aa3b
	v_writelane_b32 v249, s11, 17
	s_add_u32 s10, s84, 0xfd13d00
	s_addc_u32 s11, s85, 0
	v_writelane_b32 v249, s10, 18
	v_bfrev_b32_e32 v217, 64
	v_mov_b32_e32 v218, 32
	v_writelane_b32 v249, s11, 19
	s_add_u32 s10, s84, 0xfd13e00
	s_addc_u32 s11, s85, 0
	v_writelane_b32 v249, s10, 20
	v_mov_b32_e32 v188, 0x3f317218
	v_bfrev_b32_e32 v219, 0.5
	v_writelane_b32 v249, s11, 21
	s_add_u32 s10, s84, 0xfd13f00
	s_addc_u32 s11, s85, 0
	v_writelane_b32 v249, s10, 22
	v_mov_b32_e32 v220, 0x800
	v_mov_b32_e32 v221, 0x1000
	v_writelane_b32 v249, s11, 23
	s_add_u32 s10, s84, 0xfd14000
	s_addc_u32 s11, s85, 0
	v_writelane_b32 v249, s10, 24
	v_mov_b32_e32 v222, 0x1800
	v_mov_b32_e32 v223, 0x3db504f3
	v_writelane_b32 v249, s11, 25
	s_add_u32 s10, s84, 0xfd14100
	s_addc_u32 s11, s85, 0
	v_writelane_b32 v249, s10, 26
	v_mov_b32_e32 v224, 0x4000
	s_mov_b32 s52, 0x30000
	v_writelane_b32 v249, s11, 27
	s_add_u32 s10, s84, 0xfd14200
	s_addc_u32 s11, s85, 0
	v_writelane_b32 v249, s10, 28
	s_mov_b32 s53, 0x20000
	s_mov_b32 s54, 0x10000
	v_writelane_b32 v249, s11, 29
	s_add_u32 s10, s84, 0xfd14300
	s_addc_u32 s11, s85, 0
	v_writelane_b32 v249, s10, 30
	s_cmp_eq_u32 s16, 15
	s_movk_i32 s55, 0x1000
	v_writelane_b32 v249, s11, 31
	s_cselect_b64 s[10:11], -1, 0
	v_writelane_b32 v249, s10, 32
	s_cmp_eq_u32 s16, 14
	s_mov_b32 s56, 0x40000
	v_writelane_b32 v249, s11, 33
	s_cselect_b64 s[10:11], -1, 0
	v_writelane_b32 v249, s10, 34
	s_cmp_eq_u32 s16, 13
	s_mov_b32 s57, 0x50000
	v_writelane_b32 v249, s11, 35
	s_cselect_b64 s[10:11], -1, 0
	v_writelane_b32 v249, s10, 36
	s_cmp_eq_u32 s16, 12
	s_mov_b32 s2, 0x800000
	v_writelane_b32 v249, s11, 37
	s_cselect_b64 s[10:11], -1, 0
	v_writelane_b32 v249, s10, 38
	s_cmp_eq_u32 s16, 11
	s_movk_i32 s49, 0x80
	v_writelane_b32 v249, s11, 39
	s_cselect_b64 s[10:11], -1, 0
	v_writelane_b32 v249, s10, 40
	s_cmp_eq_u32 s16, 10
	s_mov_b32 s67, 0x41000000
	v_writelane_b32 v249, s11, 41
	s_cselect_b64 s[10:11], -1, 0
	v_writelane_b32 v249, s10, 42
	s_cmp_eq_u32 s16, 9
	s_movk_i32 s33, 0xe000
	v_writelane_b32 v249, s11, 43
	s_cselect_b64 s[10:11], -1, 0
	v_writelane_b32 v249, s10, 44
	s_cmp_eq_u32 s16, 8
	s_movk_i32 s97, 0xa000
	v_writelane_b32 v249, s11, 45
	s_cselect_b64 s[10:11], -1, 0
	v_writelane_b32 v249, s10, 46
	s_cmp_eq_u32 s16, 7
	s_mov_b32 s63, 0
	v_writelane_b32 v249, s11, 47
	v_writelane_b32 v249, s12, 48
	s_cselect_b64 s[10:11], -1, 0
	s_cmp_eq_u32 s16, 6
	v_writelane_b32 v249, s13, 49
	v_writelane_b32 v249, s10, 50
	v_cndmask_b32_e64 v207, 0, 1, s[12:13]
	s_mov_b32 s66, 0x3fd744fd
	v_writelane_b32 v249, s11, 51
	s_cselect_b64 s[10:11], -1, 0
	v_writelane_b32 v249, s10, 52
	s_cmp_eq_u32 s16, 5
	s_mov_b64 s[64:65], 0x800
; #define GLOBAL_AS __attribute__((address_space(1)))
; __global__ void __launch_bounds__(256, 2) mk(Params p_in, int ph_lo, int ph_hi) {
;     ...
;     long zoff = 0;
;     asm volatile("" : "+s"(zoff));
;     Params p;
; #pragma unroll
;     for (int i = 0; i < 21; ++i) p.in[i] = (const float*)((GLOBAL_AS const float*)(p_in.in[i]));
;     p.ws = (char*)((GLOBAL_AS char*)(p_in.ws + zoff));
;     p.out = (float*)((GLOBAL_AS float*)(p_in.out + zoff));
;     bf16_t* hb = (bf16_t*)(p.ws + OFF_HB);
;     bf16_t* wb = (bf16_t*)(p.ws + OFF_WB);
;     bf16_t* r0 = (bf16_t*)(p.ws + OFF_R0);
;     bf16_t* r1 = (bf16_t*)(p.ws + OFF_R1);
	v_writelane_b32 v249, s11, 53
	s_cselect_b64 s[10:11], -1, 0
	v_writelane_b32 v249, s10, 54
	s_cmp_eq_u32 s16, 4
	s_mov_b64 s[60:61], 0x80
	v_writelane_b32 v249, s11, 55
	s_cselect_b64 s[10:11], -1, 0
	v_writelane_b32 v249, s10, 56
	s_cmp_eq_u32 s16, 3
	s_mov_b64 s[22:23], 0x8000
	v_writelane_b32 v249, s11, 57
	s_cselect_b64 s[10:11], -1, 0
	v_writelane_b32 v249, s10, 58
	s_cmp_eq_u32 s16, 2
	s_nop 0
	v_writelane_b32 v249, s11, 59
	s_cselect_b64 s[10:11], -1, 0
	v_writelane_b32 v249, s10, 60
	s_cmp_eq_u32 s16, 1
	s_nop 0
	v_writelane_b32 v249, s11, 61
	s_cselect_b64 s[10:11], -1, 0
	v_writelane_b32 v249, s10, 62
	s_cmp_eq_u32 s16, 0
	s_nop 0
	v_writelane_b32 v249, s11, 63
	s_cselect_b64 s[10:11], -1, 0
	s_lshl_b32 s3, s16, 8
	s_add_u32 s4, s4, s3
	v_writelane_b32 v248, s10, 0
	s_addc_u32 s3, s5, 0
	s_nop 0
	v_writelane_b32 v248, s11, 1
	s_add_u32 s10, s4, 0x1400
	s_addc_u32 s11, s3, 0
	v_writelane_b32 v248, s10, 2
	s_add_u32 s4, s4, 0x2400
	s_addc_u32 s5, s3, 0
	v_writelane_b32 v248, s11, 3
	v_writelane_b32 v248, s4, 4
	s_nop 1
	v_writelane_b32 v248, s5, 5
	s_add_u32 s4, s84, 0xfd16400
	s_addc_u32 s5, s85, 0
	v_writelane_b32 v248, s4, 6
	s_nop 1
	v_writelane_b32 v248, s5, 7
	s_add_u32 s4, s84, 0xfd16500
	s_addc_u32 s5, s85, 0
	v_writelane_b32 v248, s4, 8
	s_ashr_i32 s95, s94, 31
	s_nop 0
	v_writelane_b32 v248, s5, 9
	s_mul_i32 s4, s48, 0x6000
	s_mul_hi_i32 s5, s94, 0x1800
	v_writelane_b32 v248, s4, 10
	s_nop 1
	v_writelane_b32 v248, s5, 11
	s_add_u32 s4, s84, 0x6d5b640
	s_addc_u32 s5, s85, 0
	v_writelane_b32 v248, s4, 12
	s_nop 1
	v_writelane_b32 v248, s5, 13
	s_lshl_b64 s[4:5], s[94:95], 11
	v_writelane_b32 v248, s4, 14
	s_add_u32 s3, s84, 0x6bc4800
	s_mov_b32 s95, s6
	v_writelane_b32 v248, s5, 15
	v_writelane_b32 v248, s3, 16
	s_addc_u32 s3, s85, 0
	v_writelane_b32 v248, s3, 17
	s_add_u32 s3, s84, 0x3bb3000
	v_writelane_b32 v248, s3, 18
	s_addc_u32 s3, s85, 0
	v_writelane_b32 v248, s3, 19
	s_add_u32 s3, s84, 0x5bc3000
	v_writelane_b32 v248, s3, 20
	s_addc_u32 s3, s85, 0
	v_writelane_b32 v248, s3, 21
	s_lshl_b32 s3, s48, 9
	v_writelane_b32 v248, s3, 22
	s_lshl_b32 s3, s48, 14
	s_add_u32 s4, s84, 0x1000
	v_writelane_b32 v248, s3, 23
	s_addc_u32 s5, s85, 0
	v_writelane_b32 v248, s4, 24
	s_ashr_i32 s9, s8, 31
	s_nop 0
	v_writelane_b32 v248, s5, 25
	s_mov_b32 s4, s8
	v_writelane_b32 v248, s4, 26
	s_nop 1
	v_writelane_b32 v248, s5, 27
	s_lshl_b64 s[4:5], s[8:9], 11
	v_writelane_b32 v248, s4, 28
	s_nop 1
	v_writelane_b32 v248, s5, 29
	s_load_dwordx16 s[4:19], s[0:1], 0x40
	s_waitcnt lgkmcnt(0)
	s_add_u32 s20, s4, 0x207000
	v_writelane_b32 v248, s4, 30
	s_addc_u32 s21, s5, 0
	s_lshl_b32 s3, s48, 7
	v_writelane_b32 v248, s5, 31
	v_writelane_b32 v248, s6, 32
	v_writelane_b32 v248, s7, 33
	v_writelane_b32 v248, s8, 34
	v_writelane_b32 v248, s9, 35
	v_writelane_b32 v248, s10, 36
	v_writelane_b32 v248, s11, 37
	v_writelane_b32 v248, s12, 38
	v_writelane_b32 v248, s13, 39
	v_writelane_b32 v248, s14, 40
	v_writelane_b32 v248, s15, 41
	v_writelane_b32 v248, s16, 42
	v_writelane_b32 v248, s17, 43
	v_writelane_b32 v248, s18, 44
	v_writelane_b32 v248, s19, 45
	v_writelane_b32 v248, s20, 46
	s_add_i32 s4, 32, 0x12000
	s_mov_b32 s19, 0x70000
	v_writelane_b32 v248, s21, 47
	v_writelane_b32 v248, s3, 48
	s_lshl_b32 s3, s48, 10
	v_writelane_b32 v248, s3, 49
	v_writelane_b32 v248, s4, 50
	s_load_dwordx4 s[4:7], s[0:1], 0xa0
	s_mov_b32 s3, 0x60000
	s_movk_i32 s20, 0x400
	s_movk_i32 s21, 0x800
	s_movk_i32 s12, 0xc000
	s_waitcnt lgkmcnt(0)
	v_writelane_b32 v248, s4, 51
	s_mov_b32 s8, 0x3f803f80
	s_nop 0
	v_writelane_b32 v248, s5, 52
	v_writelane_b32 v248, s6, 53
	v_writelane_b32 v248, s7, 54
	v_writelane_b32 v248, s36, 55
	s_brev_b32 s4, 1
	s_nop 0
	v_writelane_b32 v248, s37, 56
	v_writelane_b32 v248, s38, 57
	v_writelane_b32 v248, s39, 58
	v_writelane_b32 v248, s40, 59
	v_writelane_b32 v248, s41, 60
	v_writelane_b32 v248, s42, 61
	v_writelane_b32 v248, s43, 62
	v_writelane_b32 v248, s68, 63
	s_nop 1
	v_writelane_b32 v247, s69, 0
	v_writelane_b32 v247, s70, 1
	v_writelane_b32 v247, s71, 2
	v_writelane_b32 v247, s72, 3
	v_writelane_b32 v247, s73, 4
	v_writelane_b32 v247, s74, 5
	v_writelane_b32 v247, s75, 6
	v_writelane_b32 v247, s76, 7
	v_writelane_b32 v247, s77, 8
	v_writelane_b32 v247, s78, 9
	v_writelane_b32 v247, s79, 10
	v_writelane_b32 v247, s80, 11
	v_writelane_b32 v247, s81, 12
	v_writelane_b32 v247, s82, 13
	v_writelane_b32 v247, s83, 14
	v_writelane_b32 v247, s30, 15
	s_nop 1
	v_writelane_b32 v247, s31, 16
	v_writelane_b32 v247, s28, 17
	s_nop 1
	v_writelane_b32 v247, s29, 18
	s_branch .LBB0_20

; #define BIDX opaque_bid()
; #define EN(bit) if constexpr ((ENABLE >> (bit)) & 1)
;   const int nmain = 64 * nnt, ntiles = nmain + nnt;
;   const int nb = gridDim.x - skip;
;   const int b = BIDX - skip;
; __global__ void __launch_bounds__(256, 2) mk(Params p_in, int ph_lo, int ph_hi) {
;     ...
;           const int nitems = 8 * (8 / NW);
;           if ((int)BIDX < nitems) {
;             EN(7) { scan_item(p, BIDX & 7, BIDX >> 3, smem); }
;           } else {
;             EN(2) { gemm_phase(hb, 1024, wb + WB_Z, 1024, 8, smem, EpiZ{r0 + R0_Z}, nitems); }
.LBB0_352:
	s_andn2_b64 vcc, exec, s[0:1]
	s_cbranch_vccnz .LBB0_1238
	s_mov_b32 s0, s88
	s_cmp_gt_i32 s0, 63
	s_mov_b64 s[0:1], -1
	s_cbranch_scc0 .LBB0_1158
	s_add_u32 s6, s14, 0x2680000
	s_addc_u32 s7, s15, 0
	s_add_u32 s10, s14, 0x6d5b240
	s_mov_b32 s0, s88
	s_addc_u32 s11, s15, 0
	s_sub_i32 s5, s0, 64
	s_mov_b32 s9, 0
	s_branch .LBB0_358

; #define TIDX opaque_tid()
; DEVI void scan_item(const Params& p, int h, int sl, char* smem) {
;   const int tid = TIDX, lane = tid & 63, wave = tid >> 6, l15 = lane & 15, quad = lane >> 4;
;   bf16_t* r1 = (bf16_t*)(p.ws + OFF_R1);
;   const bf16_t* r0 = (const bf16_t*)(p.ws + OFF_R0);
;   char* wsm = smem;
;   char* qksm = smem + 17408;
;   char* ktsm = smem + 26624;
;   char* usm = smem + 45056;
;   float* gsm = (float*)(smem + 50176);
;   char* sbx = smem + 51200;
;   char* vbx = smem + 59392;
;   constexpr int USTR = (NW * 16 + 8) * 2;
;   const int vb0 = sl * NW * 16;
;   const bool is_state = wave < NW;
;   const int cw = is_state ? wave : wave - NW;
;   u32x4 pw[4], pqk[2], pkt[4], pg = u32x4{0, 0, 0, 0}, pu = u32x4{0, 0, 0, 0};
;     ...
;       f32x4 acco[2][NW];
; #pragma unroll
;       for (int ct = 0; ct < NW; ++ct) {
;         bf16x8 sb[4];
; #pragma unroll
;         for (int s = 0; s < 4; ++s) sb[s] = *(const bf16x8*)(sbx + ((ct * 4 + s) * 64 + lane) * 16);
; #pragma unroll
;         for (int m = 0; m < 2; ++m) acco[m][ct] = f32x4{0.f, 0.f, 0.f, 0.f};
; #pragma unroll
;         for (int s = 0; s < 4; ++s)
; #pragma unroll
;           for (int m = 0; m < 2; ++m) acco[m][ct] = MFMA16(qfr[m][s], sb[s], acco[m][ct]);
;       }
;       if (n + 1 < NCH) qload(n + 1);
;       __syncthreads();
;       const int t0 = n * 64 - 48;
; #pragma unroll
;       for (int m = 0; m < 2; ++m) {
;         const int mt = cw * 2 + m;
;         bf16x8 qkf[2];
; #pragma unroll
;         for (int s2 = 0; s2 < 2; ++s2) {
;           const char* a = qksm + (mt * 16 + l15) * 144 + s2 * 64 + quad * 8;
;           qkf[s2] = mk8(*(const u32x2*)a, *(const u32x2*)(a + 32));
;         }
;         const f32x4 ge4 = *(const f32x4*)(gsm + mt * 16 + quad * 4);
; #pragma unroll
;         for (int ct = 0; ct < NW; ++ct) {
;           f32x4 a2 = f32x4{0.f, 0.f, 0.f, 0.f};
; #pragma unroll
;           for (int s2 = 0; s2 < 2; ++s2) {
;             const bf16x8 vb = *(const bf16x8*)(vbx + ((ct * 2 + s2) * 64 + lane) * 16);
;             a2 = MFMA16(qkf[s2], vb, a2);
;           }
; #pragma unroll
;           for (int jj = 0; jj < 4; ++jj) {
;             const int t = t0 + mt * 16 + quad * 4 + jj;
;             const float o = ge4[jj] * acco[m][ct][jj] + a2[jj];
;             if (t >= 0) r1[(size_t)t * 3072 + 2048 + h * 128 + vb0 + ct * 16 + l15] = f2bf(o);
;           }
;         }
;       }
.LBB0_1158:
	s_and_b64 vcc, exec, s[0:1]
	s_cbranch_vccz .LBB0_1238
	v_lshrrev_b32_e32 v2, 6, v206
	v_and_b32_e32 v0, 63, v206
	v_readfirstlane_b32 s5, v2
	s_and_b32 s9, s88, 7
	s_lshr_b32 s13, s88, 3
	v_and_b32_e32 v3, 15, v0
	v_lshrrev_b32_e32 v4, 4, v0
	s_lshl_b32 s18, s9, 8
	s_add_u32 s0, s14, 0x9bab000
	s_addc_u32 s1, s15, 0
	s_add_u32 s0, s0, s18
	s_addc_u32 s1, s1, 0
	s_cmp_eq_u32 s5, 0
	s_cbranch_scc1 .Lsc_state
	s_cmp_eq_u32 s5, 3
	s_cbranch_scc1 .Lsc_idle
	s_sub_u32 s24, s5, 1
	s_lshl_b32 s24, s24, 1
	s_lshl_b32 s25, s24, 4
	v_add_u32_e32 v5, s25, v3
	v_mul_u32_u24_e32 v6, 0x1800, v5
	v_lshl_add_u32 v100, v4, 4, v6
	v_add_u32_e32 v100, 0x60000, v100
	v_lshlrev_b32_e32 v7, 7, v5
	v_lshl_add_u32 v102, v4, 4, v7
	v_add_u32_e32 v102, 0x10000, v102
	v_lshlrev_b32_e32 v104, 2, v5
	v_add_u32_e32 v104, 0x1800, v104
	s_lshl_b32 s36, s13, 5
	v_lshl_add_u32 v7, v4, 3, s36
	v_add_u32_e32 v7, 0x1000, v7
	v_add_u32_e32 v106, v6, v7
	v_add_u32_e32 v5, s25, v3
	v_add_u32_e32 v5, 16, v5
	v_mul_u32_u24_e32 v6, 0x1800, v5
	v_lshl_add_u32 v101, v4, 4, v6
	v_add_u32_e32 v101, 0x60000, v101
	v_lshlrev_b32_e32 v7, 7, v5
	v_lshl_add_u32 v103, v4, 4, v7
	v_add_u32_e32 v103, 0x10000, v103
	v_lshlrev_b32_e32 v105, 2, v5
	v_add_u32_e32 v105, 0x1800, v105
	s_lshl_b32 s36, s13, 5
	v_lshl_add_u32 v7, v4, 3, s36
	v_add_u32_e32 v7, 0x1000, v7
	v_add_u32_e32 v107, v6, v7
	v_lshlrev_b32_e32 v108, 4, v0
	v_add_u32_e32 v108, 6176, v108
	s_lshl_b32 s18, s9, 13
	s_add_u32 s6, s14, 0x5ba3000
	s_addc_u32 s7, s15, 0
	s_add_u32 s6, s6, s18
	s_addc_u32 s7, s7, 0
	s_mul_i32 s18, s9, 0x300
	s_add_u32 s10, s14, 0x6bc1800
	s_addc_u32 s11, s15, 0
	s_add_u32 s10, s10, s18
	s_addc_u32 s11, s11, 0
	global_load_dwordx4 v[8:11], v100, s[0:1] offset:0
	global_load_dwordx4 v[12:15], v100, s[0:1] offset:64
	global_load_dwordx4 v[16:19], v100, s[0:1] offset:128
	global_load_dwordx4 v[20:23], v100, s[0:1] offset:192
	global_load_dwordx4 v[24:27], v101, s[0:1] offset:0
	global_load_dwordx4 v[28:31], v101, s[0:1] offset:64
	global_load_dwordx4 v[32:35], v101, s[0:1] offset:128
	global_load_dwordx4 v[36:39], v101, s[0:1] offset:192
	global_load_dwordx4 v[40:43], v102, s[6:7] offset:0
	global_load_dwordx4 v[44:47], v102, s[6:7] offset:64
	global_load_dwordx4 v[48:51], v103, s[6:7] offset:0
	global_load_dwordx4 v[52:55], v103, s[6:7] offset:64
	global_load_dword v56, v104, s[10:11]
	global_load_dword v57, v105, s[10:11]
	s_mov_b32 s18, 0
	s_waitcnt vmcnt(0)
	s_barrier
.Lsc_out_loop:
	s_add_u32 s0, s0, 0x60000
	s_addc_u32 s1, s1, 0
	s_add_u32 s6, s6, 0x10000
	s_addc_u32 s7, s7, 0
	s_add_u32 s10, s10, 0x1800
	s_addc_u32 s11, s11, 0
	v_xor_b32_e32 v108, 0x1800, v108
	s_barrier
	ds_read_b128 v[60:63], v108 offset:0
	ds_read_b128 v[64:67], v108 offset:1024
	ds_read_b128 v[68:71], v108 offset:2048
	ds_read_b128 v[72:75], v108 offset:3072
	ds_read_b128 v[76:79], v108 offset:4096
	ds_read_b128 v[80:83], v108 offset:5120
	s_waitcnt vmcnt(15) lgkmcnt(5)
	v_mfma_f32_16x16x32_bf16 v[84:87], v[60:63], v[8:11], 0
	global_load_dwordx4 v[8:11], v100, s[0:1] offset:0
	s_waitcnt vmcnt(15) lgkmcnt(4)
	v_mfma_f32_16x16x32_bf16 v[84:87], v[64:67], v[12:15], v[84:87]
	global_load_dwordx4 v[12:15], v100, s[0:1] offset:64
	s_waitcnt vmcnt(15) lgkmcnt(3)
	v_mfma_f32_16x16x32_bf16 v[84:87], v[68:71], v[16:19], v[84:87]
	global_load_dwordx4 v[16:19], v100, s[0:1] offset:128
	s_waitcnt vmcnt(15) lgkmcnt(2)
	v_mfma_f32_16x16x32_bf16 v[84:87], v[72:75], v[20:23], v[84:87]
	global_load_dwordx4 v[20:23], v100, s[0:1] offset:192
	s_waitcnt vmcnt(15)
	v_mfma_f32_16x16x32_bf16 v[88:91], v[60:63], v[24:27], 0
	global_load_dwordx4 v[24:27], v101, s[0:1] offset:0
	s_waitcnt vmcnt(15)
	v_mfma_f32_16x16x32_bf16 v[88:91], v[64:67], v[28:31], v[88:91]
	global_load_dwordx4 v[28:31], v101, s[0:1] offset:64
	s_waitcnt vmcnt(15)
	v_mfma_f32_16x16x32_bf16 v[88:91], v[68:71], v[32:35], v[88:91]
	global_load_dwordx4 v[32:35], v101, s[0:1] offset:128
	s_waitcnt vmcnt(15)
	v_mfma_f32_16x16x32_bf16 v[88:91], v[72:75], v[36:39], v[88:91]
	global_load_dwordx4 v[36:39], v101, s[0:1] offset:192
	s_waitcnt vmcnt(15) lgkmcnt(1)
	v_mfma_f32_16x16x32_bf16 v[92:95], v[76:79], v[40:43], 0
	global_load_dwordx4 v[40:43], v102, s[6:7] offset:0
	s_waitcnt vmcnt(15) lgkmcnt(0)
	v_mfma_f32_16x16x32_bf16 v[92:95], v[80:83], v[44:47], v[92:95]
	global_load_dwordx4 v[44:47], v102, s[6:7] offset:64
	s_waitcnt vmcnt(15)
	v_mfma_f32_16x16x32_bf16 v[96:99], v[76:79], v[48:51], 0
	global_load_dwordx4 v[48:51], v103, s[6:7] offset:0
	s_waitcnt vmcnt(15)
	v_mfma_f32_16x16x32_bf16 v[96:99], v[80:83], v[52:55], v[96:99]
	global_load_dwordx4 v[52:55], v103, s[6:7] offset:64
	s_lshl_b32 s36, s18, 2
	s_add_u32 s36, s36, s24
	s_waitcnt vmcnt(15)
	s_nop 3
	v_fma_f32 v110, -v56, v84, v92
	v_fma_f32 v111, -v56, v85, v93
	v_fma_f32 v112, -v56, v86, v94
	v_fma_f32 v113, -v56, v87, v95
	global_load_dword v56, v104, s[10:11]
	v_cvt_pk_bf16_f32 v114, v110, v111
	v_cvt_pk_bf16_f32 v115, v112, v113
	s_cmp_lt_u32 s36, 3
	s_cbranch_scc1 .Lsc_out_skip0
	global_store_dwordx2 v106, v[114:115], s[0:1]
.Lsc_out_skip0:
	s_waitcnt vmcnt(15)
	v_fma_f32 v110, -v57, v88, v96
	v_fma_f32 v111, -v57, v89, v97
	v_fma_f32 v112, -v57, v90, v98
	v_fma_f32 v113, -v57, v91, v99
	global_load_dword v57, v105, s[10:11]
	v_cvt_pk_bf16_f32 v114, v110, v111
	v_cvt_pk_bf16_f32 v115, v112, v113
	s_cmp_lt_u32 s36, 2
	s_cbranch_scc1 .Lsc_out_skip1
	global_store_dwordx2 v107, v[114:115], s[0:1]
.Lsc_out_skip1:
	s_cmp_lg_u32 s18, 0
	s_cbranch_scc1 .Lsc_out_nodrain
	s_waitcnt vmcnt(0)
.Lsc_out_nodrain:
	s_add_u32 s18, s18, 1
	s_cmp_lt_u32 s18, 257
	s_cbranch_scc1 .Lsc_out_loop
	s_branch .Lsc_done
; DEVI void scan_item(const Params& p, int h, int sl, char* smem) {
;     ...
;     if (tid < 64 * NW * 2) {
;       const int row = tid / (NW * 2), kc = tid % (NW * 2);
;       const int t = t0 + row;
;       pu = u32x4{0, 0, 0, 0};
;       if (t >= 0) pu = *(const u32x4*)(r1 + (size_t)t * 3072 + 2048 + h * 128 + vb0 + kc * 8);
;     }
;   };
;   auto lstore = [&]() {
; #pragma unroll
;     for (int i = 0; i < 4; ++i) {
;       const int ch = tid + i * 256, row = ch >> 4, kc = ch & 15;
;       *(u32x4*)(wsm + row * 272 + kc * 16) = pw[i];
;     }
;     if (tid < 48) *(u32x4*)(gsm + tid * 4) = pg;
;     if (tid < 64 * NW * 2) {
;       const int row = tid / (NW * 2), kc = tid % (NW * 2);
;       *(u32x4*)(usm + row * USTR + kc * 16) = pu;
;     }
.Lsc_idle:
	s_lshl_b32 s40, s13, 5
	v_lshl_add_u32 v5, v3, 1, s40
	v_mul_u32_u24_e32 v6, 0x6000, v4
	v_add_u32_e32 v5, v5, v6
	v_add_u32_e32 v5, 0x61000, v5
	v_mov_b32_e32 v24, v5
	v_add_u32_e32 v25, 0x1800, v5
	v_add_u32_e32 v26, 0x3000, v5
	v_add_u32_e32 v27, 0x4800, v5
	v_lshlrev_b32_e32 v28, 4, v0
	v_add_u32_e32 v28, 16416, v28
	s_add_u32 s6, s0, 0x18000
	s_addc_u32 s7, s1, 0
	s_add_u32 s10, s0, 0x30000
	s_addc_u32 s11, s1, 0
	s_add_u32 s16, s0, 0x48000
	s_addc_u32 s17, s1, 0
	global_load_ushort v8, v24, s[0:1]
	global_load_ushort v9, v25, s[0:1]
	global_load_ushort v10, v26, s[0:1]
	global_load_ushort v11, v27, s[0:1]
	global_load_ushort v12, v24, s[6:7]
	global_load_ushort v13, v25, s[6:7]
	global_load_ushort v14, v26, s[6:7]
	global_load_ushort v15, v27, s[6:7]
	global_load_ushort v16, v24, s[10:11]
	global_load_ushort v17, v25, s[10:11]
	global_load_ushort v18, v26, s[10:11]
	global_load_ushort v19, v27, s[10:11]
	global_load_ushort v20, v24, s[16:17]
	global_load_ushort v21, v25, s[16:17]
	global_load_ushort v22, v26, s[16:17]
	global_load_ushort v23, v27, s[16:17]
	s_waitcnt vmcnt(0)
	v_mov_b32_e32 v8, 0
	v_mov_b32_e32 v9, 0
	v_mov_b32_e32 v10, 0
	v_mov_b32_e32 v11, 0
	v_mov_b32_e32 v12, 0
	v_mov_b32_e32 v13, 0
	v_mov_b32_e32 v14, 0
	v_mov_b32_e32 v15, 0
	v_mov_b32_e32 v16, 0
	v_mov_b32_e32 v17, 0
	v_mov_b32_e32 v18, 0
	v_mov_b32_e32 v19, 0
	v_lshlrev_b32_e32 v8, 16, v8
	v_lshlrev_b32_e32 v9, 16, v9
	v_lshlrev_b32_e32 v10, 16, v10
	v_lshlrev_b32_e32 v11, 16, v11
	v_lshlrev_b32_e32 v12, 16, v12
	v_lshlrev_b32_e32 v13, 16, v13
	v_lshlrev_b32_e32 v14, 16, v14
	v_lshlrev_b32_e32 v15, 16, v15
	v_lshlrev_b32_e32 v16, 16, v16
	v_lshlrev_b32_e32 v17, 16, v17
	v_lshlrev_b32_e32 v18, 16, v18
	v_lshlrev_b32_e32 v19, 16, v19
	v_lshlrev_b32_e32 v20, 16, v20
	v_lshlrev_b32_e32 v21, 16, v21
	v_lshlrev_b32_e32 v22, 16, v22
	v_lshlrev_b32_e32 v23, 16, v23
	ds_write_b128 v28, v[8:11] offset:0
	ds_write_b128 v28, v[12:15] offset:1024
	ds_write_b128 v28, v[16:19] offset:2048
	ds_write_b128 v28, v[20:23] offset:3072
	s_add_u32 s0, s0, 0x60000
	s_addc_u32 s1, s1, 0
	s_add_u32 s6, s6, 0x60000
	s_addc_u32 s7, s7, 0
	s_add_u32 s10, s10, 0x60000
	s_addc_u32 s11, s11, 0
	s_add_u32 s16, s16, 0x60000
	s_addc_u32 s17, s17, 0
	global_load_ushort v8, v24, s[0:1]
	global_load_ushort v9, v25, s[0:1]
	global_load_ushort v10, v26, s[0:1]
	global_load_ushort v11, v27, s[0:1]
	global_load_ushort v12, v24, s[6:7]
	global_load_ushort v13, v25, s[6:7]
	global_load_ushort v14, v26, s[6:7]
	global_load_ushort v15, v27, s[6:7]
	global_load_ushort v16, v24, s[10:11]
	global_load_ushort v17, v25, s[10:11]
	global_load_ushort v18, v26, s[10:11]
	global_load_ushort v19, v27, s[10:11]
	global_load_ushort v20, v24, s[16:17]
	global_load_ushort v21, v25, s[16:17]
	global_load_ushort v22, v26, s[16:17]
	global_load_ushort v23, v27, s[16:17]
	s_waitcnt lgkmcnt(0)
	s_barrier
	s_mov_b32 s18, 0
.Lsc_idle_loop:
	s_waitcnt vmcnt(0)
	v_xor_b32_e32 v28, 0x1000, v28
	v_lshlrev_b32_e32 v8, 16, v8
	v_lshlrev_b32_e32 v9, 16, v9
	v_lshlrev_b32_e32 v10, 16, v10
	v_lshlrev_b32_e32 v11, 16, v11
	v_lshlrev_b32_e32 v12, 16, v12
	v_lshlrev_b32_e32 v13, 16, v13
	v_lshlrev_b32_e32 v14, 16, v14
	v_lshlrev_b32_e32 v15, 16, v15
	v_lshlrev_b32_e32 v16, 16, v16
	v_lshlrev_b32_e32 v17, 16, v17
	v_lshlrev_b32_e32 v18, 16, v18
	v_lshlrev_b32_e32 v19, 16, v19
	v_lshlrev_b32_e32 v20, 16, v20
	v_lshlrev_b32_e32 v21, 16, v21
	v_lshlrev_b32_e32 v22, 16, v22
	v_lshlrev_b32_e32 v23, 16, v23
	ds_write_b128 v28, v[8:11] offset:0
	ds_write_b128 v28, v[12:15] offset:1024
	ds_write_b128 v28, v[16:19] offset:2048
	ds_write_b128 v28, v[20:23] offset:3072
	s_add_u32 s0, s0, 0x60000
	s_addc_u32 s1, s1, 0
	s_add_u32 s6, s6, 0x60000
	s_addc_u32 s7, s7, 0
	s_add_u32 s10, s10, 0x60000
	s_addc_u32 s11, s11, 0
	s_add_u32 s16, s16, 0x60000
	s_addc_u32 s17, s17, 0
	s_cmp_ge_u32 s18, 256
	s_cbranch_scc1 .Lsc_idle_noload
	global_load_ushort v8, v24, s[0:1]
	global_load_ushort v9, v25, s[0:1]
	global_load_ushort v10, v26, s[0:1]
	global_load_ushort v11, v27, s[0:1]
	global_load_ushort v12, v24, s[6:7]
	global_load_ushort v13, v25, s[6:7]
	global_load_ushort v14, v26, s[6:7]
	global_load_ushort v15, v27, s[6:7]
	global_load_ushort v16, v24, s[10:11]
	global_load_ushort v17, v25, s[10:11]
	global_load_ushort v18, v26, s[10:11]
	global_load_ushort v19, v27, s[10:11]
	global_load_ushort v20, v24, s[16:17]
	global_load_ushort v21, v25, s[16:17]
	global_load_ushort v22, v26, s[16:17]
	global_load_ushort v23, v27, s[16:17]
.Lsc_idle_noload:
	s_waitcnt lgkmcnt(0)
	s_barrier
	s_add_u32 s18, s18, 1
	s_cmp_lt_u32 s18, 257
	s_cbranch_scc1 .Lsc_idle_loop
	s_branch .Lsc_done
; DEVI void scan_item(const Params& p, int h, int sl, char* smem) {
;     ...
;   auto gload = [&](int n) {
;     const int t0 = n * 64 - 48;
; #pragma unroll
;     for (int i = 0; i < 4; ++i) {
;       const int ch = tid + i * 256, row = ch >> 4, kc = ch & 15;
;       const int t = t0 + row;
;       pw[i] = u32x4{0, 0, 0, 0};
;       if (t >= 0) pw[i] = *(const u32x4*)(r1 + (size_t)t * 3072 + 1024 + h * 128 + kc * 8);
;     }
;     const bf16_t* qk = r0 + R0_QK + (size_t)(n * 8 + h) * 4096;
; #pragma unroll
;     for (int i = 0; i < 2; ++i) pqk[i] = *(const u32x4*)(qk + (size_t)(tid + i * 256) * 8);
;     const bf16_t* kt = r0 + R0_KT + (size_t)(n * 8 + h) * 8192;
; #pragma unroll
;     for (int i = 0; i < 4; ++i) pkt[i] = *(const u32x4*)(kt + (size_t)(tid + i * 256) * 8);
;     if (tid < 48) pg = *(const u32x4*)((const float*)(r0 + R0_G) + (size_t)(n * 8 + h) * 192 + tid * 4);
;     if (tid < 64 * NW * 2) {
;       const int row = tid / (NW * 2), kc = tid % (NW * 2);
;       const int t = t0 + row;
;       pu = u32x4{0, 0, 0, 0};
;       if (t >= 0) pu = *(const u32x4*)(r1 + (size_t)t * 3072 + 2048 + h * 128 + vb0 + kc * 8);
;     }
;   };
;     ...
;   f32x4 S[8];
; #pragma unroll
;   for (int r = 0; r < 8; ++r) S[r] = f32x4{0.f, 0.f, 0.f, 0.f};
;   gload(0);
;   if (!is_state) qload(0);
.Lsc_state:
	s_setprio 3
	v_mul_u32_u24_e32 v5, 0x1800, v3
	v_lshl_add_u32 v187, v4, 4, v5
	v_add_u32_e32 v187, 0x60800, v187
	v_lshlrev_b32_e32 v5, 7, v3
	v_lshl_add_u32 v189, v4, 4, v5
	v_add_u32_e32 v189, 0x20000, v189
	v_lshlrev_b32_e32 v225, 4, v4
	v_add_u32_e32 v225, 0x1900, v225
	v_lshlrev_b32_e32 v246, 4, v0
	v_add_u32_e32 v246, 6176, v246
	v_lshlrev_b32_e32 v245, 4, v0
	v_add_u32_e32 v245, 16416, v245
	s_add_u32 s6, s0, 0x18000
	s_addc_u32 s7, s1, 0
	s_add_u32 s10, s0, 0x30000
	s_addc_u32 s11, s1, 0
	s_add_u32 s16, s0, 0x48000
	s_addc_u32 s17, s1, 0
	s_lshl_b32 s18, s9, 14
	s_add_u32 s24, s14, 0x3b74000
	s_addc_u32 s25, s15, 0
	s_add_u32 s24, s24, s18
	s_addc_u32 s25, s25, 0
	s_add_u32 s36, s24, 0x2000
	s_addc_u32 s37, s25, 0
	s_mul_i32 s18, s9, 0x300
	s_add_u32 s38, s14, 0x6bc1800
	s_addc_u32 s39, s15, 0
	s_add_u32 s38, s38, s18
	s_addc_u32 s39, s39, 0
	v_mov_b32_e32 v2, 0
	v_mov_b32_e32 v3, 0
	v_mov_b32_e32 v4, 0
	v_mov_b32_e32 v5, 0
	v_mov_b32_e32 v6, 0
	v_mov_b32_e32 v7, 0
	v_mov_b32_e32 v8, 0
	v_mov_b32_e32 v9, 0
	v_mov_b32_e32 v10, 0
	v_mov_b32_e32 v11, 0
	v_mov_b32_e32 v12, 0
	v_mov_b32_e32 v13, 0
	v_mov_b32_e32 v14, 0
	v_mov_b32_e32 v15, 0
	v_mov_b32_e32 v16, 0
	v_mov_b32_e32 v17, 0
	v_mov_b32_e32 v18, 0
	v_mov_b32_e32 v19, 0
	v_mov_b32_e32 v20, 0
	v_mov_b32_e32 v21, 0
	v_mov_b32_e32 v22, 0
	v_mov_b32_e32 v23, 0
	v_mov_b32_e32 v24, 0
	v_mov_b32_e32 v25, 0
	v_mov_b32_e32 v26, 0
	v_mov_b32_e32 v27, 0
	v_mov_b32_e32 v28, 0
	v_mov_b32_e32 v29, 0
	v_mov_b32_e32 v30, 0
	v_mov_b32_e32 v31, 0
	v_mov_b32_e32 v32, 0
	v_mov_b32_e32 v33, 0
	global_load_dwordx4 v[34:37], v187, s[0:1] offset:0
	global_load_dwordx4 v[38:41], v187, s[0:1] offset:64
	global_load_dwordx4 v[42:45], v187, s[0:1] offset:128
	global_load_dwordx4 v[46:49], v187, s[0:1] offset:192
	global_load_dwordx4 v[50:53], v187, s[6:7] offset:0
	global_load_dwordx4 v[54:57], v187, s[6:7] offset:64
	global_load_dwordx4 v[58:61], v187, s[6:7] offset:128
	global_load_dwordx4 v[62:65], v187, s[6:7] offset:192
	global_load_dwordx4 v[66:69], v187, s[10:11] offset:0
	global_load_dwordx4 v[70:73], v187, s[10:11] offset:64
	global_load_dwordx4 v[74:77], v187, s[10:11] offset:128
	global_load_dwordx4 v[78:81], v187, s[10:11] offset:192
	global_load_dwordx4 v[82:85], v187, s[16:17] offset:0
	global_load_dwordx4 v[86:89], v187, s[16:17] offset:64
	global_load_dwordx4 v[90:93], v187, s[16:17] offset:128
	global_load_dwordx4 v[94:97], v187, s[16:17] offset:192
	global_load_dwordx4 v[98:101], v189, s[24:25] offset:-4096
	global_load_dwordx4 v[102:105], v189, s[24:25] offset:-4032
	global_load_dwordx4 v[106:109], v189, s[24:25] offset:-2048
	global_load_dwordx4 v[110:113], v189, s[24:25] offset:-1984
	global_load_dwordx4 v[114:117], v189, s[24:25] offset:0
	global_load_dwordx4 v[118:121], v189, s[24:25] offset:64
	global_load_dwordx4 v[122:125], v189, s[24:25] offset:2048
	global_load_dwordx4 v[126:129], v189, s[24:25] offset:2112
	global_load_dwordx4 v[130:133], v189, s[36:37] offset:-4096
	global_load_dwordx4 v[134:137], v189, s[36:37] offset:-4032
	global_load_dwordx4 v[138:141], v189, s[36:37] offset:-2048
	global_load_dwordx4 v[142:145], v189, s[36:37] offset:-1984
	global_load_dwordx4 v[146:149], v189, s[36:37] offset:0
	global_load_dwordx4 v[150:153], v189, s[36:37] offset:64
	global_load_dwordx4 v[154:157], v189, s[36:37] offset:2048
	global_load_dwordx4 v[158:161], v189, s[36:37] offset:2112
	global_load_dwordx4 v[226:229], v225, s[38:39] offset:0
	global_load_dwordx4 v[230:233], v225, s[38:39] offset:64
	global_load_dwordx4 v[234:237], v225, s[38:39] offset:128
	global_load_dwordx4 v[238:241], v225, s[38:39] offset:192
	s_load_dword s62, s[38:39], 0x1a00
	s_waitcnt vmcnt(0) lgkmcnt(0)
	v_mov_b32_e32 v34, 0
	v_mov_b32_e32 v35, 0
	v_mov_b32_e32 v36, 0
	v_mov_b32_e32 v37, 0
	v_mov_b32_e32 v38, 0
	v_mov_b32_e32 v39, 0
	v_mov_b32_e32 v40, 0
	v_mov_b32_e32 v41, 0
	v_mov_b32_e32 v42, 0
	v_mov_b32_e32 v43, 0
	v_mov_b32_e32 v44, 0
	v_mov_b32_e32 v45, 0
	v_mov_b32_e32 v46, 0
	v_mov_b32_e32 v47, 0
	v_mov_b32_e32 v48, 0
	v_mov_b32_e32 v49, 0
	v_mov_b32_e32 v50, 0
	v_mov_b32_e32 v51, 0
	v_mov_b32_e32 v52, 0
	v_mov_b32_e32 v53, 0
	v_mov_b32_e32 v54, 0
	v_mov_b32_e32 v55, 0
	v_mov_b32_e32 v56, 0
	v_mov_b32_e32 v57, 0
	v_mov_b32_e32 v58, 0
	v_mov_b32_e32 v59, 0
	v_mov_b32_e32 v60, 0
	v_mov_b32_e32 v61, 0
	v_mov_b32_e32 v62, 0
	v_mov_b32_e32 v63, 0
	v_mov_b32_e32 v64, 0
	v_mov_b32_e32 v65, 0
	v_mov_b32_e32 v66, 0
	v_mov_b32_e32 v67, 0
	v_mov_b32_e32 v68, 0
	v_mov_b32_e32 v69, 0
	v_mov_b32_e32 v70, 0
	v_mov_b32_e32 v71, 0
	v_mov_b32_e32 v72, 0
	v_mov_b32_e32 v73, 0
	v_mov_b32_e32 v74, 0
	v_mov_b32_e32 v75, 0
	v_mov_b32_e32 v76, 0
	v_mov_b32_e32 v77, 0
	v_mov_b32_e32 v78, 0
	v_mov_b32_e32 v79, 0
	v_mov_b32_e32 v80, 0
	v_mov_b32_e32 v81, 0
	s_barrier
	ds_read_b128 v[190:193], v245 offset:0
	ds_read_b128 v[194:197], v245 offset:1024
	ds_read_b128 v[198:201], v245 offset:2048
	ds_read_b128 v[202:205], v245 offset:3072
	s_mov_b32 s18, 0
; DEVI float bf2f(bf16_t b) { return __uint_as_float(((unsigned)b) << 16); }
; #define MFMA16(a, b, c) __builtin_amdgcn_mfma_f32_16x16x32_bf16((a), (b), (c), 0, 0, 0)
; DEVI void scan_item(const Params& p, int h, int sl, char* smem) {
;     ...
;     if (is_state) {
; #pragma unroll
;       for (int s = 0; s < 4; ++s) *(bf16x8*)(sbx + ((cw * 4 + s) * 64 + lane) * 16) = pack8(S[2 * s], S[2 * s + 1]);
;     }
;     __syncthreads();
;     lstore2();
;     if (n + 1 < NCH) gload(n + 1);
;     if (is_state) {
;       bf16x8 sb[4];
; #pragma unroll
;       for (int s = 0; s < 4; ++s) sb[s] = pack8(S[2 * s], S[2 * s + 1]);
;       f32x4 vnew[4];
; #pragma unroll
;       for (int mt = 0; mt < 4; ++mt) vnew[mt] = f32x4{0.f, 0.f, 0.f, 0.f};
; #pragma unroll
;       for (int s = 0; s < 4; ++s) {
; #pragma unroll
;         for (int mt = 0; mt < 4; ++mt) {
;           const char* aw = wsm + (mt * 16 + l15) * 272 + s * 64 + quad * 8;
;           bf16x8 wf = mk8(*(const u32x2*)aw, *(const u32x2*)(aw + 32));
;           vnew[mt] = MFMA16(wf, sb[s], vnew[mt]);
;         }
;       }
; #pragma unroll
;       for (int mt = 0; mt < 4; ++mt) {
; #pragma unroll
;         for (int jj = 0; jj < 4; ++jj) {
;           const int cidx = mt * 16 + quad * 4 + jj;
;           const float u = bf2f(*(const unsigned short*)(usm + cidx * USTR + (cw * 16 + l15) * 2));
;           vnew[mt][jj] = u - vnew[mt][jj];
;         }
;       }
; #pragma unroll
;       for (int s2 = 0; s2 < 2; ++s2)
;         *(bf16x8*)(vbx + ((cw * 2 + s2) * 64 + lane) * 16) = pack8(vnew[2 * s2], vnew[2 * s2 + 1]);
;       __syncthreads();
;       const float eglast = gsm[128];
;       bf16x8 vb[2];
; #pragma unroll
;       for (int mt = 0; mt < 4; ++mt) {
;         const f32x4 gd4 = *(const f32x4*)(gsm + 64 + mt * 16 + quad * 4);
;         vnew[mt] = vnew[mt] * gd4;
;       }
; #pragma unroll
;       for (int s2 = 0; s2 < 2; ++s2) vb[s2] = pack8(vnew[2 * s2], vnew[2 * s2 + 1]);
; #pragma unroll
;       for (int r = 0; r < 8; ++r) S[r] = S[r] * eglast;
.Lsc_st_loop:
	s_add_u32 s0, s0, 0x60000
	s_addc_u32 s1, s1, 0
	s_add_u32 s6, s6, 0x60000
	s_addc_u32 s7, s7, 0
	s_add_u32 s10, s10, 0x60000
	s_addc_u32 s11, s11, 0
	s_add_u32 s16, s16, 0x60000
	s_addc_u32 s17, s17, 0
	s_add_u32 s24, s24, 0x20000
	s_addc_u32 s25, s25, 0
	s_add_u32 s36, s36, 0x20000
	s_addc_u32 s37, s37, 0
	s_add_u32 s38, s38, 0x1800
	s_addc_u32 s39, s39, 0
	v_xor_b32_e32 v246, 0x1800, v246
	v_cvt_pk_bf16_f32 v162, v2, v3
	v_cvt_pk_bf16_f32 v163, v4, v5
	v_cvt_pk_bf16_f32 v164, v6, v7
	v_cvt_pk_bf16_f32 v165, v8, v9
	ds_write_b128 v246, v[162:165] offset:0
	v_cvt_pk_bf16_f32 v166, v10, v11
	v_cvt_pk_bf16_f32 v167, v12, v13
	v_cvt_pk_bf16_f32 v168, v14, v15
	v_cvt_pk_bf16_f32 v169, v16, v17
	ds_write_b128 v246, v[166:169] offset:1024
	v_cvt_pk_bf16_f32 v170, v18, v19
	v_cvt_pk_bf16_f32 v171, v20, v21
	v_cvt_pk_bf16_f32 v172, v22, v23
	v_cvt_pk_bf16_f32 v173, v24, v25
	ds_write_b128 v246, v[170:173] offset:2048
	v_cvt_pk_bf16_f32 v174, v26, v27
	v_cvt_pk_bf16_f32 v175, v28, v29
	v_cvt_pk_bf16_f32 v176, v30, v31
	v_cvt_pk_bf16_f32 v177, v32, v33
	ds_write_b128 v246, v[174:177] offset:3072
	s_waitcnt vmcnt(35) lgkmcnt(4)
	v_mfma_f32_16x16x32_bf16 v[190:193], v[34:37], v[162:165], v[190:193]
	global_load_dwordx4 v[34:37], v187, s[0:1] offset:0
	v_mul_f32_e32 v2, s62, v2
	v_mul_f32_e32 v3, s62, v3
	s_waitcnt vmcnt(35)
	v_mfma_f32_16x16x32_bf16 v[194:197], v[50:53], v[162:165], v[194:197]
	global_load_dwordx4 v[50:53], v187, s[6:7] offset:0
	v_mul_f32_e32 v4, s62, v4
	v_mul_f32_e32 v5, s62, v5
	s_waitcnt vmcnt(35)
	v_mfma_f32_16x16x32_bf16 v[190:193], v[38:41], v[166:169], v[190:193]
	global_load_dwordx4 v[38:41], v187, s[0:1] offset:64
	v_mul_f32_e32 v6, s62, v6
	v_mul_f32_e32 v7, s62, v7
	s_waitcnt vmcnt(35)
	v_mfma_f32_16x16x32_bf16 v[194:197], v[54:57], v[166:169], v[194:197]
	global_load_dwordx4 v[54:57], v187, s[6:7] offset:64
	v_mul_f32_e32 v8, s62, v8
	v_mul_f32_e32 v9, s62, v9
	s_waitcnt vmcnt(35)
	v_mfma_f32_16x16x32_bf16 v[190:193], v[42:45], v[170:173], v[190:193]
	global_load_dwordx4 v[42:45], v187, s[0:1] offset:128
	v_mul_f32_e32 v10, s62, v10
	v_mul_f32_e32 v11, s62, v11
	s_waitcnt vmcnt(35)
	v_mfma_f32_16x16x32_bf16 v[194:197], v[58:61], v[170:173], v[194:197]
	global_load_dwordx4 v[58:61], v187, s[6:7] offset:128
	v_mul_f32_e32 v12, s62, v12
	v_mul_f32_e32 v13, s62, v13
	s_waitcnt vmcnt(35)
	v_mfma_f32_16x16x32_bf16 v[198:201], v[66:69], v[162:165], v[198:201]
	global_load_dwordx4 v[66:69], v187, s[10:11] offset:0
	v_mul_f32_e32 v14, s62, v14
	v_mul_f32_e32 v15, s62, v15
	s_waitcnt vmcnt(35)
	v_mfma_f32_16x16x32_bf16 v[202:205], v[82:85], v[162:165], v[202:205]
	global_load_dwordx4 v[82:85], v187, s[16:17] offset:0
	v_mul_f32_e32 v16, s62, v16
	v_mul_f32_e32 v17, s62, v17
	s_waitcnt vmcnt(35)
	v_mfma_f32_16x16x32_bf16 v[198:201], v[70:73], v[166:169], v[198:201]
	global_load_dwordx4 v[70:73], v187, s[10:11] offset:64
	v_mul_f32_e32 v18, s62, v18
	v_mul_f32_e32 v19, s62, v19
	s_waitcnt vmcnt(35)
	v_mfma_f32_16x16x32_bf16 v[202:205], v[86:89], v[166:169], v[202:205]
	global_load_dwordx4 v[86:89], v187, s[16:17] offset:64
	v_mul_f32_e32 v20, s62, v20
	v_mul_f32_e32 v21, s62, v21
	s_waitcnt vmcnt(35)
	v_mfma_f32_16x16x32_bf16 v[198:201], v[74:77], v[170:173], v[198:201]
	global_load_dwordx4 v[74:77], v187, s[10:11] offset:128
	v_mul_f32_e32 v22, s62, v22
	v_mul_f32_e32 v23, s62, v23
	s_waitcnt vmcnt(35)
	v_mfma_f32_16x16x32_bf16 v[202:205], v[90:93], v[170:173], v[202:205]
	global_load_dwordx4 v[90:93], v187, s[16:17] offset:128
	v_mul_f32_e32 v24, s62, v24
	v_mul_f32_e32 v25, s62, v25
	s_waitcnt vmcnt(35)
	v_mfma_f32_16x16x32_bf16 v[190:193], v[46:49], v[174:177], v[190:193]
	global_load_dwordx4 v[46:49], v187, s[0:1] offset:192
	v_mul_f32_e32 v26, s62, v26
	v_mul_f32_e32 v27, s62, v27
	s_waitcnt vmcnt(35)
	v_mfma_f32_16x16x32_bf16 v[194:197], v[62:65], v[174:177], v[194:197]
	global_load_dwordx4 v[62:65], v187, s[6:7] offset:192
	v_mul_f32_e32 v28, s62, v28
	v_mul_f32_e32 v29, s62, v29
	s_waitcnt vmcnt(35)
	v_mfma_f32_16x16x32_bf16 v[198:201], v[78:81], v[174:177], v[198:201]
	global_load_dwordx4 v[78:81], v187, s[10:11] offset:192
	v_mul_f32_e32 v30, s62, v30
	v_mul_f32_e32 v31, s62, v31
	s_waitcnt vmcnt(35)
	v_mfma_f32_16x16x32_bf16 v[202:205], v[94:97], v[174:177], v[202:205]
	global_load_dwordx4 v[94:97], v187, s[16:17] offset:192
	v_mul_f32_e32 v32, s62, v32
	v_mul_f32_e32 v33, s62, v33
	s_load_dword s62, s[38:39], 0x1a00
	s_nop 1
	s_waitcnt vmcnt(35)
; DEVI float bf2f(bf16_t b) { return __uint_as_float(((unsigned)b) << 16); }
; #define MFMA16(a, b, c) __builtin_amdgcn_mfma_f32_16x16x32_bf16((a), (b), (c), 0, 0, 0)
; DEVI void scan_item(const Params& p, int h, int sl, char* smem) {
;     ...
; #pragma unroll
;       for (int mt = 0; mt < 4; ++mt) {
; #pragma unroll
;         for (int jj = 0; jj < 4; ++jj) {
;           const int cidx = mt * 16 + quad * 4 + jj;
;           const float u = bf2f(*(const unsigned short*)(usm + cidx * USTR + (cw * 16 + l15) * 2));
;           vnew[mt][jj] = u - vnew[mt][jj];
;         }
;       }
; #pragma unroll
;       for (int s2 = 0; s2 < 2; ++s2)
;         *(bf16x8*)(vbx + ((cw * 2 + s2) * 64 + lane) * 16) = pack8(vnew[2 * s2], vnew[2 * s2 + 1]);
;       __syncthreads();
;       const float eglast = gsm[128];
;       bf16x8 vb[2];
; #pragma unroll
;       for (int mt = 0; mt < 4; ++mt) {
;         const f32x4 gd4 = *(const f32x4*)(gsm + 64 + mt * 16 + quad * 4);
;         vnew[mt] = vnew[mt] * gd4;
;       }
; #pragma unroll
;       for (int s2 = 0; s2 < 2; ++s2) vb[s2] = pack8(vnew[2 * s2], vnew[2 * s2 + 1]);
; #pragma unroll
;       for (int r = 0; r < 8; ++r) S[r] = S[r] * eglast;
; #pragma unroll
;       for (int s2 = 0; s2 < 2; ++s2) {
; #pragma unroll
;         for (int r = 0; r < 8; ++r) {
;           const char* ap = ktsm + (r * 16 + l15) * 144 + s2 * 64 + quad * 8;
;           bf16x8 f = mk8(*(const u32x2*)ap, *(const u32x2*)(ap + 32));
;           S[r] = MFMA16(f, vb[s2], S[r]);
;         }
;       }
	v_cvt_pk_bf16_f32 v162, v190, v191
	v_cvt_pk_bf16_f32 v163, v192, v193
	v_mul_f32_e64 v190, -v190, v226
	v_mul_f32_e64 v191, -v191, v227
	v_mul_f32_e64 v192, -v192, v228
	v_mul_f32_e64 v193, -v193, v229
	global_load_dwordx4 v[226:229], v225, s[38:39] offset:0
	v_cvt_pk_bf16_f32 v170, v190, v191
	v_cvt_pk_bf16_f32 v171, v192, v193
	s_waitcnt vmcnt(35)
	v_cvt_pk_bf16_f32 v164, v194, v195
	v_cvt_pk_bf16_f32 v165, v196, v197
	v_mul_f32_e64 v194, -v194, v230
	v_mul_f32_e64 v195, -v195, v231
	v_mul_f32_e64 v196, -v196, v232
	v_mul_f32_e64 v197, -v197, v233
	global_load_dwordx4 v[230:233], v225, s[38:39] offset:64
	v_cvt_pk_bf16_f32 v172, v194, v195
	v_cvt_pk_bf16_f32 v173, v196, v197
	ds_write_b128 v246, v[162:165] offset:4096
	s_nop 0
	s_waitcnt vmcnt(35)
	v_mfma_f32_16x16x32_bf16 v[2:5], v[98:101], v[170:173], v[2:5]
	global_load_dwordx4 v[98:101], v189, s[24:25] offset:-4096
	s_waitcnt vmcnt(35)
	v_mfma_f32_16x16x32_bf16 v[6:9], v[106:109], v[170:173], v[6:9]
	global_load_dwordx4 v[106:109], v189, s[24:25] offset:-2048
	s_waitcnt vmcnt(35)
	v_mfma_f32_16x16x32_bf16 v[10:13], v[114:117], v[170:173], v[10:13]
	global_load_dwordx4 v[114:117], v189, s[24:25] offset:0
	s_waitcnt vmcnt(35)
	v_mfma_f32_16x16x32_bf16 v[14:17], v[122:125], v[170:173], v[14:17]
	global_load_dwordx4 v[122:125], v189, s[24:25] offset:2048
	s_waitcnt vmcnt(35)
	v_cvt_pk_bf16_f32 v166, v198, v199
	v_cvt_pk_bf16_f32 v167, v200, v201
	v_mul_f32_e64 v198, -v198, v234
	v_mul_f32_e64 v199, -v199, v235
	v_mul_f32_e64 v200, -v200, v236
	v_mul_f32_e64 v201, -v201, v237
	global_load_dwordx4 v[234:237], v225, s[38:39] offset:128
	v_cvt_pk_bf16_f32 v174, v198, v199
	v_cvt_pk_bf16_f32 v175, v200, v201
	s_waitcnt vmcnt(35)
	v_cvt_pk_bf16_f32 v168, v202, v203
	v_cvt_pk_bf16_f32 v169, v204, v205
	v_mul_f32_e64 v202, -v202, v238
	v_mul_f32_e64 v203, -v203, v239
	v_mul_f32_e64 v204, -v204, v240
	v_mul_f32_e64 v205, -v205, v241
	global_load_dwordx4 v[238:241], v225, s[38:39] offset:192
	v_cvt_pk_bf16_f32 v176, v202, v203
	v_cvt_pk_bf16_f32 v177, v204, v205
	ds_write_b128 v246, v[166:169] offset:5120
	s_waitcnt vmcnt(35)
	v_mfma_f32_16x16x32_bf16 v[18:21], v[130:133], v[170:173], v[18:21]
	global_load_dwordx4 v[130:133], v189, s[36:37] offset:-4096
	s_waitcnt vmcnt(35)
	v_mfma_f32_16x16x32_bf16 v[22:25], v[138:141], v[170:173], v[22:25]
	global_load_dwordx4 v[138:141], v189, s[36:37] offset:-2048
	s_waitcnt vmcnt(35)
	v_mfma_f32_16x16x32_bf16 v[26:29], v[146:149], v[170:173], v[26:29]
	global_load_dwordx4 v[146:149], v189, s[36:37] offset:0
	s_waitcnt vmcnt(35)
	v_mfma_f32_16x16x32_bf16 v[30:33], v[154:157], v[170:173], v[30:33]
	global_load_dwordx4 v[154:157], v189, s[36:37] offset:2048
	s_waitcnt lgkmcnt(0)
	s_barrier
	v_xor_b32_e32 v245, 0x1000, v245
	ds_read_b128 v[190:193], v245 offset:0
	ds_read_b128 v[194:197], v245 offset:1024
	ds_read_b128 v[198:201], v245 offset:2048
	ds_read_b128 v[202:205], v245 offset:3072
	s_waitcnt vmcnt(35)
	v_mfma_f32_16x16x32_bf16 v[2:5], v[102:105], v[174:177], v[2:5]
	global_load_dwordx4 v[102:105], v189, s[24:25] offset:-4032
	s_waitcnt vmcnt(35)
	v_mfma_f32_16x16x32_bf16 v[6:9], v[110:113], v[174:177], v[6:9]
	global_load_dwordx4 v[110:113], v189, s[24:25] offset:-1984
	s_waitcnt vmcnt(35)
	v_mfma_f32_16x16x32_bf16 v[10:13], v[118:121], v[174:177], v[10:13]
	global_load_dwordx4 v[118:121], v189, s[24:25] offset:64
	s_waitcnt vmcnt(35)
	v_mfma_f32_16x16x32_bf16 v[14:17], v[126:129], v[174:177], v[14:17]
	global_load_dwordx4 v[126:129], v189, s[24:25] offset:2112
	s_waitcnt vmcnt(35)
	v_mfma_f32_16x16x32_bf16 v[18:21], v[134:137], v[174:177], v[18:21]
	global_load_dwordx4 v[134:137], v189, s[36:37] offset:-4032
	s_waitcnt vmcnt(35)
	v_mfma_f32_16x16x32_bf16 v[22:25], v[142:145], v[174:177], v[22:25]
	global_load_dwordx4 v[142:145], v189, s[36:37] offset:-1984
	s_waitcnt vmcnt(35)
	v_mfma_f32_16x16x32_bf16 v[26:29], v[150:153], v[174:177], v[26:29]
	global_load_dwordx4 v[150:153], v189, s[36:37] offset:64
	s_waitcnt vmcnt(35)
	v_mfma_f32_16x16x32_bf16 v[30:33], v[158:161], v[174:177], v[30:33]
	global_load_dwordx4 v[158:161], v189, s[36:37] offset:2112
	s_cmp_eq_u32 s18, 256
	s_cbranch_scc1 .Lsc_st_last
	s_add_u32 s18, s18, 1
	s_branch .Lsc_st_loop
.Lsc_st_last:
	s_setprio 0
.Lsc_done:
	s_waitcnt vmcnt(0) lgkmcnt(0)
